# hand-scheduled window + cmp pass2 attention loops: batched LUT reads, DPP quad sums, in-place K/V prefetch
# speedup vs baseline: 1.0176x; 1.0176x over previous
; #define LAS __attribute__((address_space(3)))
; __device__ __forceinline__ float fexp(float x) { return __expf(x); }
; __device__ __forceinline__ void nsa_wave(CArgs* Ap, int l, int b, int g, int tq0, const LAS float* lut, LAS float* imp, int lane) {
;     ...
;         float lt = st.l; lt += __shfl_xor(lt, 16); lt += __shfl_xor(lt, 32);
;         const float inv = 1.f / fmaxf(lt, 1e-30f), mfin = st.m;
;         for (int cb = 0; cb < ncb; ++cb) {
;             bf16x8 kf[4][2]; load_k(kf, KC + (size_t)cb * 4096, lane);
;             bf16x8 vf[4][2]; load_v(vf, VCT + (size_t)cb * 4096, lane);
;             f32x4 acc[4];
; #pragma unroll
;             for (int nt = 0; nt < 4; ++nt) acc[nt] = (f32x4){0.f, 0.f, 0.f, 0.f};
;             qk_acc(acc, kf, qB);
; #pragma unroll
;             for (int nt = 0; nt < 4; ++nt) {
;                 f32x4 pi4;
; #pragma unroll
;                 for (int i = 0; i < 4; ++i) {
;                     const int key = cb * 64 + 16 * nt + 4 * g4 + i; const int dist = t - (16 * key + 31);
;                     int dc = dist < 0 ? 0 : dist; dc = dc > 1023 ? 1023 : dc;
;                     const float lg = acc[nt][i] + lutg[dc * 4];
;                     float p = (dist >= 0) ? fexp(lg - mfin) * inv : 0.f;
;                     acc[nt][i] = p;
;                     p += __shfl_xor(p, 1); p += __shfl_xor(p, 2);
;                     pi4[i] = p;
;                 }
;                 if (r == 0) *(LAS f32x4*)(imp + qi * 512 + cb * 64 + 16 * nt + 4 * g4) = pi4;
.LBB0_900:
	v_lshlrev_b32_e32 v207, 6, v20
	v_cmp_lt_i32_e32 vcc, v21, v77
	v_mov_b32_e32 v19, 0
	v_xor_b32_e32 v79, 1, v74
	v_cndmask_b32_e32 v9, v74, v21, vcc
	v_lshlrev_b32_e32 v209, 2, v9
	ds_bpermute_b32 v9, v209, v8
	v_cmp_lt_i32_e32 vcc, v22, v77
	v_xor_b32_e32 v78, 2, v74
	v_cmp_lt_i32_e64 s[48:49], v79, v77
	v_cndmask_b32_e32 v10, v74, v22, vcc
	v_lshlrev_b32_e32 v208, 2, v10
	s_waitcnt lgkmcnt(0)
	v_add_f32_e32 v24, v8, v9
	ds_bpermute_b32 v25, v208, v24
	s_andn2_b64 vcc, exec, s[96:97]
	v_cmp_lt_i32_e64 s[46:47], v78, v77
	v_mov_b32_e32 v18, v19
	v_mov_b32_e32 v17, v19
	v_mov_b32_e32 v16, v19
	v_mov_b32_e32 v11, v19
	v_mov_b32_e32 v10, v19
	v_mov_b32_e32 v9, v19
	v_mov_b32_e32 v8, v19
	v_mov_b32_e32 v15, v19
	v_mov_b32_e32 v14, v19
	v_mov_b32_e32 v13, v19
	v_mov_b32_e32 v12, v19
	v_mov_b32_e32 v23, v19
	v_mov_b32_e32 v22, v19
	v_mov_b32_e32 v21, v19
	v_mov_b32_e32 v20, v19
	s_cbranch_vccnz .LBB0_943
	s_waitcnt lgkmcnt(0)
	v_add_f32_e32 v8, v24, v25
	v_max_f32_e32 v8, 0xda24260, v8
	v_div_scale_f32 v9, s[0:1], v8, v8, 1.0
	v_rcp_f32_e32 v10, v9
	v_div_scale_f32 v11, vcc, 1.0, v8, 1.0
	s_add_i32 s0, s20, s17
	v_fma_f32 v12, -v9, v10, 1.0
	v_fmac_f32_e32 v10, v12, v10
	v_mul_f32_e32 v12, v11, v10
	v_fma_f32 v13, -v9, v12, v11
	v_fmac_f32_e32 v12, v13, v10
	v_fma_f32 v9, -v9, v12, v11
	v_div_fmas_f32 v9, v9, v10, v12
	v_div_fixup_f32 v80, v9, v8, 1.0
	s_lshl_b32 s21, s21, 8
	s_ashr_i32 s1, s0, 31
	s_addk_i32 s21, 0x100
	s_lshl_b64 s[0:1], s[0:1], 16
	s_add_u32 s0, s15, s0
	s_addc_u32 s1, s16, s1
	s_mov_b32 s22, 0
	v_mov_b32_e32 v8, 0
	v_mov_b32_e32 v9, 0
	v_mov_b32_e32 v10, 0
	v_mov_b32_e32 v11, 0
	v_mov_b32_e32 v12, 0
	v_mov_b32_e32 v13, 0
	v_mov_b32_e32 v14, 0
	v_mov_b32_e32 v15, 0
	v_mov_b32_e32 v16, 0
	v_mov_b32_e32 v17, 0
	v_mov_b32_e32 v18, 0
	v_mov_b32_e32 v19, 0
	v_mov_b32_e32 v20, 0
	v_mov_b32_e32 v21, 0
	v_mov_b32_e32 v22, 0
	v_mov_b32_e32 v23, 0
	v_lshl_add_u64 v[126:127], s[0:1], 0, v[84:85]
	s_mov_b32 s23, 0x2a201000
	v_add_co_u32_e32 v120, vcc, s23, v126
	s_mov_b32 s23, 0x2a601000
	s_nop 0
	v_addc_co_u32_e32 v121, vcc, 0, v127, vcc
	v_add_co_u32_e32 v122, vcc, s23, v126
	v_add_u32_e32 v124, 0x10000, v203
	s_mov_b64 s[0:1], 0x2000
	v_addc_co_u32_e32 v123, vcc, 0, v127, vcc
	global_load_dwordx4 v[24:27], v[120:121], off offset:-4096
	global_load_dwordx4 v[28:31], v[120:121], off offset:-3072
	global_load_dwordx4 v[32:35], v[120:121], off offset:-2048
	global_load_dwordx4 v[36:39], v[120:121], off offset:-1024
	global_load_dwordx4 v[40:43], v[120:121], off offset:0
	global_load_dwordx4 v[44:47], v[120:121], off offset:1024
	global_load_dwordx4 v[48:51], v[120:121], off offset:2048
	global_load_dwordx4 v[52:55], v[120:121], off offset:3072
	global_load_dwordx4 v[56:59], v[122:123], off offset:-4096
	global_load_dwordx4 v[60:63], v[122:123], off offset:-3072
	global_load_dwordx4 v[64:67], v[122:123], off offset:-2048
	global_load_dwordx4 v[68:71], v[122:123], off offset:-1024
	global_load_dwordx4 v[100:103], v[122:123], off offset:0
	global_load_dwordx4 v[104:107], v[122:123], off offset:1024
	global_load_dwordx4 v[108:111], v[122:123], off offset:2048
	global_load_dwordx4 v[112:115], v[122:123], off offset:3072
.Lc2_loop:
	v_add_u32_e32 v244, 0x330, v75
	v_cmp_lt_i32_e64 s[46:47], -1, v244
	v_min_u32_e32 v244, v181, v244
	v_lshl_add_u32 v244, v244, 4, v206
	ds_read_b32 v244, v244
	v_add_u32_e32 v245, 0x320, v75
	v_cmp_lt_i32_e64 s[48:49], -1, v245
	v_min_u32_e32 v245, v181, v245
	v_lshl_add_u32 v245, v245, 4, v206
	ds_read_b32 v245, v245
	v_add_u32_e32 v246, 0x310, v75
	v_cmp_lt_i32_e64 s[50:51], -1, v246
	v_min_u32_e32 v246, v181, v246
	v_lshl_add_u32 v246, v246, 4, v206
	ds_read_b32 v246, v246
	v_add_u32_e32 v247, 0x300, v75
	v_cmp_lt_i32_e64 s[52:53], -1, v247
	v_min_u32_e32 v247, v181, v247
	v_lshl_add_u32 v247, v247, 4, v206
	ds_read_b32 v247, v247
	v_add_u32_e32 v248, 0x230, v75
	v_cmp_lt_i32_e64 s[54:55], -1, v248
	v_min_u32_e32 v248, v181, v248
	v_lshl_add_u32 v248, v248, 4, v206
	ds_read_b32 v248, v248
	v_add_u32_e32 v249, 0x220, v75
	v_cmp_lt_i32_e64 s[56:57], -1, v249
	v_min_u32_e32 v249, v181, v249
	v_lshl_add_u32 v249, v249, 4, v206
	ds_read_b32 v249, v249
	v_add_u32_e32 v250, 0x210, v75
	v_cmp_lt_i32_e64 s[58:59], -1, v250
	v_min_u32_e32 v250, v181, v250
	v_lshl_add_u32 v250, v250, 4, v206
	ds_read_b32 v250, v250
	v_add_u32_e32 v251, 0x200, v75
	v_cmp_lt_i32_e64 s[60:61], -1, v251
	v_min_u32_e32 v251, v181, v251
	v_lshl_add_u32 v251, v251, 4, v206
	ds_read_b32 v251, v251
	v_add_u32_e32 v252, 0x130, v75
	v_cmp_lt_i32_e64 s[62:63], -1, v252
	v_min_u32_e32 v252, v181, v252
	v_lshl_add_u32 v252, v252, 4, v206
	ds_read_b32 v252, v252
	v_add_u32_e32 v253, 0x120, v75
	v_cmp_lt_i32_e64 s[64:65], -1, v253
	v_min_u32_e32 v253, v181, v253
	v_lshl_add_u32 v253, v253, 4, v206
	ds_read_b32 v253, v253
	v_add_u32_e32 v255, 0x110, v75
	v_cmp_lt_i32_e64 s[66:67], -1, v255
	v_min_u32_e32 v255, v181, v255
	v_lshl_add_u32 v255, v255, 4, v206
	ds_read_b32 v255, v255
	v_add_u32_e32 v98, 0x100, v75
	v_cmp_lt_i32_e64 s[68:69], -1, v98
	v_min_u32_e32 v98, v181, v98
	v_lshl_add_u32 v98, v98, 4, v206
	ds_read_b32 v98, v98
	v_add_u32_e32 v99, 0x30, v75
	v_cmp_lt_i32_e64 s[96:97], -1, v99
	v_min_u32_e32 v99, v181, v99
	v_lshl_add_u32 v99, v99, 4, v206
	ds_read_b32 v99, v99
	v_add_u32_e32 v116, 0x20, v75
	v_cmp_lt_i32_e64 s[98:99], -1, v116
	v_min_u32_e32 v116, v181, v116
	v_lshl_add_u32 v116, v116, 4, v206
	ds_read_b32 v116, v116
	v_add_u32_e32 v117, 0x10, v75
	v_cmp_lt_i32_e64 s[100:101], -1, v117
	v_min_u32_e32 v117, v181, v117
	v_lshl_add_u32 v117, v117, 4, v206
	ds_read_b32 v117, v117
	v_add_u32_e32 v118, 0x0, v75
	v_cmp_lt_i32_e64 s[76:77], -1, v118
	v_min_u32_e32 v118, v181, v118
	v_lshl_add_u32 v118, v118, 4, v206
	ds_read_b32 v118, v118
	v_add_u32_e32 v75, 0xfffffc00, v75
	s_addk_i32 s22, 0x100
	s_waitcnt vmcnt(8)
	v_mfma_f32_16x16x32_bf16 v[228:231], v[24:27], v[0:3], 0
	v_mfma_f32_16x16x32_bf16 v[232:235], v[32:35], v[0:3], 0
	v_mfma_f32_16x16x32_bf16 v[236:239], v[40:43], v[0:3], 0
	v_mfma_f32_16x16x32_bf16 v[240:243], v[48:51], v[0:3], 0
	v_mfma_f32_16x16x32_bf16 v[228:231], v[28:31], v[4:7], v[228:231]
	v_mfma_f32_16x16x32_bf16 v[232:235], v[36:39], v[4:7], v[232:235]
	v_mfma_f32_16x16x32_bf16 v[236:239], v[44:47], v[4:7], v[236:239]
	v_mfma_f32_16x16x32_bf16 v[240:243], v[52:55], v[4:7], v[240:243]
	s_cmp_lg_u32 s22, s21
	s_cbranch_scc0 .Lc2_nokpf
	v_lshl_add_u64 v[120:121], v[120:121], 0, s[0:1]
	v_lshl_add_u64 v[122:123], v[122:123], 0, s[0:1]
	global_load_dwordx4 v[24:27], v[120:121], off offset:-4096
	global_load_dwordx4 v[28:31], v[120:121], off offset:-3072
	global_load_dwordx4 v[32:35], v[120:121], off offset:-2048
	global_load_dwordx4 v[36:39], v[120:121], off offset:-1024
	global_load_dwordx4 v[40:43], v[120:121], off offset:0
	global_load_dwordx4 v[44:47], v[120:121], off offset:1024
	global_load_dwordx4 v[48:51], v[120:121], off offset:2048
	global_load_dwordx4 v[52:55], v[120:121], off offset:3072
; #define LAS __attribute__((address_space(3)))
; __device__ __forceinline__ unsigned pk2(float lo, float hi) { return pg8::cvt_pk_bf16(lo, hi); }
; __device__ __forceinline__ float fexp(float x) { return __expf(x); }
; __device__ __forceinline__ void nsa_wave(CArgs* Ap, int l, int b, int g, int tq0, const LAS float* lut, LAS float* imp, int lane) {
;     ...
;                 for (int i = 0; i < 4; ++i) {
;                     const int key = cb * 64 + 16 * nt + 4 * g4 + i; const int dist = t - (16 * key + 31);
;                     int dc = dist < 0 ? 0 : dist; dc = dc > 1023 ? 1023 : dc;
;                     const float lg = acc[nt][i] + lutg[dc * 4];
;                     float p = (dist >= 0) ? fexp(lg - mfin) * inv : 0.f;
;                     acc[nt][i] = p;
;                     p += __shfl_xor(p, 1); p += __shfl_xor(p, 2);
;                     pi4[i] = p;
;                 }
;                 if (r == 0) *(LAS f32x4*)(imp + qi * 512 + cb * 64 + 16 * nt + 4 * g4) = pi4;
;             }
; #pragma unroll
;             for (int hh = 0; hh < 2; ++hh) { u32x4 w; w.x = pk2(acc[2 * hh][0], acc[2 * hh][1]); w.y = pk2(acc[2 * hh][2], acc[2 * hh][3]); w.z = pk2(acc[2 * hh + 1][0], acc[2 * hh + 1][1]); w.w = pk2(acc[2 * hh + 1][2], acc[2 * hh + 1][3]);
;                 pB[hh] = __builtin_bit_cast(bf16x8, w); }
.Lc2_nokpf:
	s_waitcnt lgkmcnt(0)
	s_nop 7
	v_add_f32_e32 v244, v228, v244
	v_add_f32_e32 v245, v229, v245
	v_add_f32_e32 v246, v230, v246
	v_add_f32_e32 v247, v231, v247
	v_add_f32_e32 v248, v232, v248
	v_add_f32_e32 v249, v233, v249
	v_add_f32_e32 v250, v234, v250
	v_add_f32_e32 v251, v235, v251
	v_add_f32_e32 v252, v236, v252
	v_add_f32_e32 v253, v237, v253
	v_add_f32_e32 v255, v238, v255
	v_add_f32_e32 v98, v239, v98
	v_add_f32_e32 v99, v240, v99
	v_add_f32_e32 v116, v241, v116
	v_add_f32_e32 v117, v242, v117
	v_add_f32_e32 v118, v243, v118
	v_sub_f32_e32 v244, v244, v76
	v_sub_f32_e32 v245, v245, v76
	v_sub_f32_e32 v246, v246, v76
	v_sub_f32_e32 v247, v247, v76
	v_sub_f32_e32 v248, v248, v76
	v_sub_f32_e32 v249, v249, v76
	v_sub_f32_e32 v250, v250, v76
	v_sub_f32_e32 v251, v251, v76
	v_sub_f32_e32 v252, v252, v76
	v_sub_f32_e32 v253, v253, v76
	v_sub_f32_e32 v255, v255, v76
	v_sub_f32_e32 v98, v98, v76
	v_sub_f32_e32 v99, v99, v76
	v_sub_f32_e32 v116, v116, v76
	v_sub_f32_e32 v117, v117, v76
	v_sub_f32_e32 v118, v118, v76
	v_mul_f32_e32 v244, 0x3fb8aa3b, v244
	v_mul_f32_e32 v245, 0x3fb8aa3b, v245
	v_mul_f32_e32 v246, 0x3fb8aa3b, v246
	v_mul_f32_e32 v247, 0x3fb8aa3b, v247
	v_mul_f32_e32 v248, 0x3fb8aa3b, v248
	v_mul_f32_e32 v249, 0x3fb8aa3b, v249
	v_mul_f32_e32 v250, 0x3fb8aa3b, v250
	v_mul_f32_e32 v251, 0x3fb8aa3b, v251
	v_mul_f32_e32 v252, 0x3fb8aa3b, v252
	v_mul_f32_e32 v253, 0x3fb8aa3b, v253
	v_mul_f32_e32 v255, 0x3fb8aa3b, v255
	v_mul_f32_e32 v98, 0x3fb8aa3b, v98
	v_mul_f32_e32 v99, 0x3fb8aa3b, v99
	v_mul_f32_e32 v116, 0x3fb8aa3b, v116
	v_mul_f32_e32 v117, 0x3fb8aa3b, v117
	v_mul_f32_e32 v118, 0x3fb8aa3b, v118
	v_exp_f32_e32 v244, v244
	v_exp_f32_e32 v245, v245
	v_exp_f32_e32 v246, v246
	v_exp_f32_e32 v247, v247
	v_exp_f32_e32 v248, v248
	v_exp_f32_e32 v249, v249
	v_exp_f32_e32 v250, v250
	v_exp_f32_e32 v251, v251
	v_exp_f32_e32 v252, v252
	v_exp_f32_e32 v253, v253
	v_exp_f32_e32 v255, v255
	v_exp_f32_e32 v98, v98
	v_exp_f32_e32 v99, v99
	v_exp_f32_e32 v116, v116
	v_exp_f32_e32 v117, v117
	v_exp_f32_e32 v118, v118
	v_mul_f32_e32 v244, v80, v244
	v_mul_f32_e32 v245, v80, v245
	v_mul_f32_e32 v246, v80, v246
	v_mul_f32_e32 v247, v80, v247
	v_mul_f32_e32 v248, v80, v248
	v_mul_f32_e32 v249, v80, v249
	v_mul_f32_e32 v250, v80, v250
	v_mul_f32_e32 v251, v80, v251
	v_mul_f32_e32 v252, v80, v252
	v_mul_f32_e32 v253, v80, v253
	v_mul_f32_e32 v255, v80, v255
	v_mul_f32_e32 v98, v80, v98
	v_mul_f32_e32 v99, v80, v99
	v_mul_f32_e32 v116, v80, v116
	v_mul_f32_e32 v117, v80, v117
	v_mul_f32_e32 v118, v80, v118
	v_cndmask_b32_e64 v244, 0, v244, s[46:47]
	v_cndmask_b32_e64 v245, 0, v245, s[48:49]
	v_cndmask_b32_e64 v246, 0, v246, s[50:51]
	v_cndmask_b32_e64 v247, 0, v247, s[52:53]
	v_cndmask_b32_e64 v248, 0, v248, s[54:55]
	v_cndmask_b32_e64 v249, 0, v249, s[56:57]
	v_cndmask_b32_e64 v250, 0, v250, s[58:59]
	v_cndmask_b32_e64 v251, 0, v251, s[60:61]
	v_cndmask_b32_e64 v252, 0, v252, s[62:63]
	v_cndmask_b32_e64 v253, 0, v253, s[64:65]
	v_cndmask_b32_e64 v255, 0, v255, s[66:67]
	v_cndmask_b32_e64 v98, 0, v98, s[68:69]
	v_cndmask_b32_e64 v99, 0, v99, s[96:97]
	v_cndmask_b32_e64 v116, 0, v116, s[98:99]
	v_cndmask_b32_e64 v117, 0, v117, s[100:101]
	v_cndmask_b32_e64 v118, 0, v118, s[76:77]
	v_add_f32_dpp v228, v244, v244 quad_perm:[1,0,3,2] row_mask:0xf bank_mask:0xf
	v_add_f32_dpp v229, v245, v245 quad_perm:[1,0,3,2] row_mask:0xf bank_mask:0xf
	v_add_f32_dpp v230, v246, v246 quad_perm:[1,0,3,2] row_mask:0xf bank_mask:0xf
	v_add_f32_dpp v231, v247, v247 quad_perm:[1,0,3,2] row_mask:0xf bank_mask:0xf
	v_add_f32_dpp v232, v248, v248 quad_perm:[1,0,3,2] row_mask:0xf bank_mask:0xf
	v_add_f32_dpp v233, v249, v249 quad_perm:[1,0,3,2] row_mask:0xf bank_mask:0xf
	v_add_f32_dpp v234, v250, v250 quad_perm:[1,0,3,2] row_mask:0xf bank_mask:0xf
	v_add_f32_dpp v235, v251, v251 quad_perm:[1,0,3,2] row_mask:0xf bank_mask:0xf
	v_add_f32_dpp v236, v252, v252 quad_perm:[1,0,3,2] row_mask:0xf bank_mask:0xf
	v_add_f32_dpp v237, v253, v253 quad_perm:[1,0,3,2] row_mask:0xf bank_mask:0xf
	v_add_f32_dpp v238, v255, v255 quad_perm:[1,0,3,2] row_mask:0xf bank_mask:0xf
	v_add_f32_dpp v239, v98, v98 quad_perm:[1,0,3,2] row_mask:0xf bank_mask:0xf
	v_add_f32_dpp v240, v99, v99 quad_perm:[1,0,3,2] row_mask:0xf bank_mask:0xf
	v_add_f32_dpp v241, v116, v116 quad_perm:[1,0,3,2] row_mask:0xf bank_mask:0xf
	v_add_f32_dpp v242, v117, v117 quad_perm:[1,0,3,2] row_mask:0xf bank_mask:0xf
	v_add_f32_dpp v243, v118, v118 quad_perm:[1,0,3,2] row_mask:0xf bank_mask:0xf
	v_add_f32_dpp v228, v228, v228 quad_perm:[2,3,0,1] row_mask:0xf bank_mask:0xf
	v_add_f32_dpp v229, v229, v229 quad_perm:[2,3,0,1] row_mask:0xf bank_mask:0xf
	v_add_f32_dpp v230, v230, v230 quad_perm:[2,3,0,1] row_mask:0xf bank_mask:0xf
	v_add_f32_dpp v231, v231, v231 quad_perm:[2,3,0,1] row_mask:0xf bank_mask:0xf
	v_add_f32_dpp v232, v232, v232 quad_perm:[2,3,0,1] row_mask:0xf bank_mask:0xf
	v_add_f32_dpp v233, v233, v233 quad_perm:[2,3,0,1] row_mask:0xf bank_mask:0xf
	v_add_f32_dpp v234, v234, v234 quad_perm:[2,3,0,1] row_mask:0xf bank_mask:0xf
	v_add_f32_dpp v235, v235, v235 quad_perm:[2,3,0,1] row_mask:0xf bank_mask:0xf
	v_add_f32_dpp v236, v236, v236 quad_perm:[2,3,0,1] row_mask:0xf bank_mask:0xf
	v_add_f32_dpp v237, v237, v237 quad_perm:[2,3,0,1] row_mask:0xf bank_mask:0xf
	v_add_f32_dpp v238, v238, v238 quad_perm:[2,3,0,1] row_mask:0xf bank_mask:0xf
	v_add_f32_dpp v239, v239, v239 quad_perm:[2,3,0,1] row_mask:0xf bank_mask:0xf
	v_add_f32_dpp v240, v240, v240 quad_perm:[2,3,0,1] row_mask:0xf bank_mask:0xf
	v_add_f32_dpp v241, v241, v241 quad_perm:[2,3,0,1] row_mask:0xf bank_mask:0xf
	v_add_f32_dpp v242, v242, v242 quad_perm:[2,3,0,1] row_mask:0xf bank_mask:0xf
	v_add_f32_dpp v243, v243, v243 quad_perm:[2,3,0,1] row_mask:0xf bank_mask:0xf
	s_mov_b64 exec, s[2:3]
	ds_write_b128 v124, v[228:231]
	ds_write_b128 v124, v[232:235] offset:64
	ds_write_b128 v124, v[236:239] offset:128
	ds_write_b128 v124, v[240:243] offset:192
	s_mov_b64 exec, -1
	v_add_u32_e32 v124, 0x100, v124
	v_cvt_pk_bf16_f32 v244, v244, v245
	v_cvt_pk_bf16_f32 v245, v246, v247
	v_cvt_pk_bf16_f32 v246, v248, v249
	v_cvt_pk_bf16_f32 v247, v250, v251
	v_cvt_pk_bf16_f32 v248, v252, v253
	v_cvt_pk_bf16_f32 v249, v255, v98
	v_cvt_pk_bf16_f32 v250, v99, v116
	v_cvt_pk_bf16_f32 v251, v117, v118
	s_cmp_lg_u32 s22, s21
	s_cbranch_scc0 .Lc2_last
; __device__ __forceinline__ unsigned pk2(float lo, float hi) { return pg8::cvt_pk_bf16(lo, hi); }
; __device__ __forceinline__ void nsa_wave(CArgs* Ap, int l, int b, int g, int tq0, const LAS float* lut, LAS float* imp, int lane) {
;     ...
; #pragma unroll
;             for (int hh = 0; hh < 2; ++hh) { u32x4 w; w.x = pk2(acc[2 * hh][0], acc[2 * hh][1]); w.y = pk2(acc[2 * hh][2], acc[2 * hh][3]); w.z = pk2(acc[2 * hh + 1][0], acc[2 * hh + 1][1]); w.w = pk2(acc[2 * hh + 1][2], acc[2 * hh + 1][3]);
;                 pB[hh] = __builtin_bit_cast(bf16x8, w); }
;             pv_acc(outacc, vf, pB);
;         }
	s_waitcnt vmcnt(8)
	v_mfma_f32_16x16x32_bf16 v[16:19], v[56:59], v[244:247], v[16:19]
	v_mfma_f32_16x16x32_bf16 v[20:23], v[64:67], v[244:247], v[20:23]
	v_mfma_f32_16x16x32_bf16 v[12:15], v[100:103], v[244:247], v[12:15]
	v_mfma_f32_16x16x32_bf16 v[8:11], v[108:111], v[244:247], v[8:11]
	v_mfma_f32_16x16x32_bf16 v[16:19], v[60:63], v[248:251], v[16:19]
	v_mfma_f32_16x16x32_bf16 v[20:23], v[68:71], v[248:251], v[20:23]
	v_mfma_f32_16x16x32_bf16 v[12:15], v[104:107], v[248:251], v[12:15]
	v_mfma_f32_16x16x32_bf16 v[8:11], v[112:115], v[248:251], v[8:11]
	global_load_dwordx4 v[56:59], v[122:123], off offset:-4096
	global_load_dwordx4 v[60:63], v[122:123], off offset:-3072
	global_load_dwordx4 v[64:67], v[122:123], off offset:-2048
	global_load_dwordx4 v[68:71], v[122:123], off offset:-1024
	global_load_dwordx4 v[100:103], v[122:123], off offset:0
	global_load_dwordx4 v[104:107], v[122:123], off offset:1024
	global_load_dwordx4 v[108:111], v[122:123], off offset:2048
	global_load_dwordx4 v[112:115], v[122:123], off offset:3072
	s_branch .Lc2_loop
.Lc2_last:
	s_waitcnt vmcnt(0)
	s_nop 0
	v_mfma_f32_16x16x32_bf16 v[16:19], v[56:59], v[244:247], v[16:19]
	v_mfma_f32_16x16x32_bf16 v[20:23], v[64:67], v[244:247], v[20:23]
	v_mfma_f32_16x16x32_bf16 v[12:15], v[100:103], v[244:247], v[12:15]
	v_mfma_f32_16x16x32_bf16 v[8:11], v[108:111], v[244:247], v[8:11]
	v_mfma_f32_16x16x32_bf16 v[16:19], v[60:63], v[248:251], v[16:19]
	v_mfma_f32_16x16x32_bf16 v[20:23], v[68:71], v[248:251], v[20:23]
	v_mfma_f32_16x16x32_bf16 v[12:15], v[104:107], v[248:251], v[12:15]
	v_mfma_f32_16x16x32_bf16 v[8:11], v[112:115], v[248:251], v[8:11]
	s_nop 7
	s_branch .LBB0_943

; __device__ __forceinline__ void nsa_wave(CArgs* Ap, int l, int b, int g, int tq0, const LAS float* lut, LAS float* imp, int lane) {
;     ...
;         float lt = st.l; lt += __shfl_xor(lt, 16); lt += __shfl_xor(lt, 32);
;         const float sc = gt[1] / (P8_SCALE * fmaxf(lt, 1e-30f));
; #pragma unroll
;         for (int dt = 0; dt < 4; ++dt) outacc[dt] = Od[dt] * sc;
;     }
;     {
;         SmState st{-1e30f, 0.f};
;         f32x4 Od[4];
; #pragma unroll
;         for (int dt = 0; dt < 4; ++dt) Od[dt] = (f32x4){0.f, 0.f, 0.f, 0.f};
;         const bf16_t* Kw = (const bf16_t*)(ws + WS_KWT) + (size_t)(b * 4 + g) * 128 * 4096;
;         const int lo = tq0 - 511, jb0 = (lo > 0 ? lo : 0) >> 6, jb1 = (tq0 + 3) >> 6;
;         for (int jb = jb0; jb <= jb1; ++jb) {
;             bf16x8 kf[4][2]; load_k(kf, Kw + (size_t)jb * 4096, lane);
;             bf16x8 vf[4][2]; load_v(vf, VWT + (size_t)jb * 4096, lane);
;             f32x4 acc[4];
; #pragma unroll
;             for (int nt = 0; nt < 4; ++nt) acc[nt] = (f32x4){0.f, 0.f, 0.f, 0.f};
;             qk_acc(acc, kf, qB);
.LBB0_1280:
	ds_bpermute_b32 v24, v209, v215
	s_max_i32 s0, s19, 0x1ff
	s_addk_i32 s0, 0xfe01
	s_waitcnt vmcnt(5)
	v_mov_b32_e32 v39, 0
	s_lshr_b32 s72, s0, 6
	s_waitcnt lgkmcnt(0)
	v_add_f32_e32 v100, v215, v24
	ds_bpermute_b32 v101, v208, v100
	s_cmp_le_i32 s72, s21
	v_mov_b32_e32 v38, v39
	s_waitcnt vmcnt(3)
	v_mov_b32_e32 v37, v39
	v_mov_b32_e32 v36, v39
	v_mov_b32_e32 v35, v39
	v_mov_b32_e32 v34, v39
	v_mov_b32_e32 v33, v39
	v_mov_b32_e32 v32, v39
	v_mov_b32_e32 v31, v39
	v_mov_b32_e32 v30, v39
	v_mov_b32_e32 v29, v39
	v_mov_b32_e32 v28, v39
	v_mov_b32_e32 v27, v39
	v_mov_b32_e32 v26, v39
	v_mov_b32_e32 v25, v39
	v_mov_b32_e32 v24, v39
	v_mov_b32_e32 v72, v39
	s_cbranch_scc0 .LBB0_892
	v_add_u32_e32 v127, s18, v204
	s_add_i32 s18, s20, s17
	s_ashr_i32 s19, s18, 31
	s_add_i32 s0, s72, -1
	s_lshl_b32 s1, s72, 6
	s_lshl_b64 s[18:19], s[18:19], 20
	s_lshl_b64 s[22:23], s[72:73], 13
	s_add_u32 s18, s18, s22
	s_addc_u32 s19, s19, s23
	v_subrev_u32_e32 v102, s1, v127
	v_lshl_add_u64 v[98:99], v[90:91], 0, s[18:19]
	s_movk_i32 s18, 0xf400
	s_mov_b32 s19, -1
	v_mov_b32_e32 v103, 0xf149f2ca
	v_lshl_add_u64 v[98:99], v[98:99], 0, s[18:19]
	v_mov_b32_e32 v126, 0
	v_add_co_u32_e32 v124, vcc, 0xfd200000, v98
	s_mov_b64 s[18:19], 0x2000
	s_nop 0
	v_addc_co_u32_e32 v125, vcc, -1, v99, vcc
	global_load_dwordx4 v[40:43], v[98:99], off offset:-4096
	global_load_dwordx4 v[44:47], v[98:99], off offset:-3072
	global_load_dwordx4 v[48:51], v[98:99], off offset:-2048
	global_load_dwordx4 v[52:55], v[98:99], off offset:-1024
	global_load_dwordx4 v[56:59], v[98:99], off offset:0
	global_load_dwordx4 v[60:63], v[98:99], off offset:1024
	global_load_dwordx4 v[64:67], v[98:99], off offset:2048
	global_load_dwordx4 v[68:71], v[98:99], off offset:3072
	global_load_dwordx4 v[72:75], v[124:125], off offset:-4096
	global_load_dwordx4 v[76:79], v[124:125], off offset:-3072
	global_load_dwordx4 v[80:83], v[124:125], off offset:-2048
	global_load_dwordx4 v[104:107], v[124:125], off offset:-1024
	global_load_dwordx4 v[108:111], v[124:125], off offset:0
	global_load_dwordx4 v[112:115], v[124:125], off offset:1024
	global_load_dwordx4 v[116:119], v[124:125], off offset:2048
	global_load_dwordx4 v[120:123], v[124:125], off offset:3072
.Lwin_loop:
	v_add_u32_e32 v244, 51, v102
	v_cmp_gt_u32_e64 s[46:47], s78, v244
	v_med3_i32 v244, v244, 0, v181
	v_lshl_add_u32 v244, v244, 4, v206
	ds_read_b32 v244, v244
	v_add_u32_e32 v245, 50, v102
	v_cmp_gt_u32_e64 s[48:49], s78, v245
	v_med3_i32 v245, v245, 0, v181
	v_lshl_add_u32 v245, v245, 4, v206
	ds_read_b32 v245, v245
	v_add_u32_e32 v246, 49, v102
	v_cmp_gt_u32_e64 s[50:51], s78, v246
	v_med3_i32 v246, v246, 0, v181
	v_lshl_add_u32 v246, v246, 4, v206
	ds_read_b32 v246, v246
	v_add_u32_e32 v247, 48, v102
	v_cmp_gt_u32_e64 s[52:53], s78, v247
	v_med3_i32 v247, v247, 0, v181
	v_lshl_add_u32 v247, v247, 4, v206
	ds_read_b32 v247, v247
	v_add_u32_e32 v248, 35, v102
	v_cmp_gt_u32_e64 s[54:55], s78, v248
	v_med3_i32 v248, v248, 0, v181
	v_lshl_add_u32 v248, v248, 4, v206
	ds_read_b32 v248, v248
	v_add_u32_e32 v249, 34, v102
	v_cmp_gt_u32_e64 s[56:57], s78, v249
	v_med3_i32 v249, v249, 0, v181
	v_lshl_add_u32 v249, v249, 4, v206
	ds_read_b32 v249, v249
	v_add_u32_e32 v250, 33, v102
	v_cmp_gt_u32_e64 s[58:59], s78, v250
	v_med3_i32 v250, v250, 0, v181
	v_lshl_add_u32 v250, v250, 4, v206
	ds_read_b32 v250, v250
	v_add_u32_e32 v251, 32, v102
	v_cmp_gt_u32_e64 s[60:61], s78, v251
	v_med3_i32 v251, v251, 0, v181
	v_lshl_add_u32 v251, v251, 4, v206
	ds_read_b32 v251, v251
	v_add_u32_e32 v252, 19, v102
	v_cmp_gt_u32_e64 s[62:63], s78, v252
	v_med3_i32 v252, v252, 0, v181
	v_lshl_add_u32 v252, v252, 4, v206
	ds_read_b32 v252, v252
	v_add_u32_e32 v253, 18, v102
	v_cmp_gt_u32_e64 s[64:65], s78, v253
	v_med3_i32 v253, v253, 0, v181
	v_lshl_add_u32 v253, v253, 4, v206
	ds_read_b32 v253, v253
	v_add_u32_e32 v210, 17, v102
	v_cmp_gt_u32_e64 s[66:67], s78, v210
	v_med3_i32 v210, v210, 0, v181
	v_lshl_add_u32 v210, v210, 4, v206
	ds_read_b32 v210, v210
	v_add_u32_e32 v211, 16, v102
	v_cmp_gt_u32_e64 s[68:69], s78, v211
	v_med3_i32 v211, v211, 0, v181
	v_lshl_add_u32 v211, v211, 4, v206
	ds_read_b32 v211, v211
	v_add_u32_e32 v212, 3, v102
	v_cmp_gt_u32_e64 s[96:97], s78, v212
	v_med3_i32 v212, v212, 0, v181
	v_lshl_add_u32 v212, v212, 4, v206
	ds_read_b32 v212, v212
	v_add_u32_e32 v213, 2, v102
	v_cmp_gt_u32_e64 s[98:99], s78, v213
	v_med3_i32 v213, v213, 0, v181
	v_lshl_add_u32 v213, v213, 4, v206
	ds_read_b32 v213, v213
	v_add_u32_e32 v144, 1, v102
	v_cmp_gt_u32_e64 s[100:101], s78, v144
	v_med3_i32 v144, v144, 0, v181
	v_lshl_add_u32 v144, v144, 4, v206
	ds_read_b32 v144, v144
	v_add_u32_e32 v255, 0, v102
	v_cmp_gt_u32_e64 s[22:23], s78, v255
	v_med3_i32 v255, v255, 0, v181
	v_lshl_add_u32 v255, v255, 4, v206
	ds_read_b32 v255, v255
	v_subrev_u32_e32 v102, 64, v102
	s_add_i32 s0, s0, 1
	s_waitcnt vmcnt(8)
	v_mfma_f32_16x16x32_bf16 v[228:231], v[40:43], v[0:3], 0
	v_mfma_f32_16x16x32_bf16 v[232:235], v[48:51], v[0:3], 0
	v_mfma_f32_16x16x32_bf16 v[236:239], v[56:59], v[0:3], 0
	v_mfma_f32_16x16x32_bf16 v[240:243], v[64:67], v[0:3], 0
	v_mfma_f32_16x16x32_bf16 v[228:231], v[44:47], v[4:7], v[228:231]
	v_mfma_f32_16x16x32_bf16 v[232:235], v[52:55], v[4:7], v[232:235]
	v_mfma_f32_16x16x32_bf16 v[236:239], v[60:63], v[4:7], v[236:239]
	v_mfma_f32_16x16x32_bf16 v[240:243], v[68:71], v[4:7], v[240:243]
	s_cmp_lt_i32 s0, s21
	s_cbranch_scc0 .Lwin_nokpf
	v_lshl_add_u64 v[98:99], v[98:99], 0, s[18:19]
	v_lshl_add_u64 v[124:125], v[124:125], 0, s[18:19]
	global_load_dwordx4 v[40:43], v[98:99], off offset:-4096
	global_load_dwordx4 v[44:47], v[98:99], off offset:-3072
	global_load_dwordx4 v[48:51], v[98:99], off offset:-2048
	global_load_dwordx4 v[52:55], v[98:99], off offset:-1024
	global_load_dwordx4 v[56:59], v[98:99], off offset:0
	global_load_dwordx4 v[60:63], v[98:99], off offset:1024
	global_load_dwordx4 v[64:67], v[98:99], off offset:2048
	global_load_dwordx4 v[68:71], v[98:99], off offset:3072
; #define LAS __attribute__((address_space(3)))
; __device__ __forceinline__ unsigned pk2(float lo, float hi) { return pg8::cvt_pk_bf16(lo, hi); }
; __device__ __forceinline__ float fexp(float x) { return __expf(x); }
; template <int MODE>
; __device__ __forceinline__ void softmax_block(f32x4 (&acc)[4], int base, bool ok, int t, int g4, const LAS float* lutg, SmState& st, f32x4 (&O)[4], bf16x8 (&pB)[2]) {
;     float mx = -1e30f; unsigned vm = 0u;
; #pragma unroll
;     for (int nt = 0; nt < 4; ++nt)
; #pragma unroll
;         for (int i = 0; i < 4; ++i) {
;             const int key = base + 16 * nt + 4 * g4 + i;
;             const int dist = (MODE == 0) ? t - (16 * key + 31) : t - key;
;             bool valid = dist >= 0;
;             if (MODE == 1) valid = valid && ok;
;             if (MODE == 2) valid = valid && dist < 512;
;             int dc = dist < 0 ? 0 : dist; dc = dc > 1023 ? 1023 : dc;
;             const float lg = acc[nt][i] + lutg[dc * 4];
;             acc[nt][i] = lg;
;             if (valid) { mx = fmaxf(mx, lg); vm |= 1u << (nt * 4 + i); }
;         }
;     mx = fmaxf(mx, __shfl_xor(mx, 16)); mx = fmaxf(mx, __shfl_xor(mx, 32));
;     const float mn = fmaxf(st.m, mx);
;     const float sc = fexp(st.m - mn);
;     float ls = 0.f;
; #pragma unroll
;     for (int nt = 0; nt < 4; ++nt)
; #pragma unroll
;         for (int i = 0; i < 4; ++i) { const float p = ((vm >> (nt * 4 + i)) & 1u) ? fexp(acc[nt][i] - mn) : 0.f; acc[nt][i] = p; ls += p; }
;     st.l = st.l * sc + ls; st.m = mn;
; #pragma unroll
;     for (int dt = 0; dt < 4; ++dt) O[dt] = O[dt] * sc;
; #pragma unroll
;     for (int hh = 0; hh < 2; ++hh) { u32x4 w; w.x = pk2(acc[2 * hh][0], acc[2 * hh][1]); w.y = pk2(acc[2 * hh][2], acc[2 * hh][3]); w.z = pk2(acc[2 * hh + 1][0], acc[2 * hh + 1][1]); w.w = pk2(acc[2 * hh + 1][2], acc[2 * hh + 1][3]);
;         pB[hh] = __builtin_bit_cast(bf16x8, w); }
.Lwin_nokpf:
	s_waitcnt lgkmcnt(0)
	s_nop 7
	v_add_f32_e32 v228, v228, v244
	v_add_f32_e32 v229, v229, v245
	v_add_f32_e32 v230, v230, v246
	v_add_f32_e32 v231, v231, v247
	v_add_f32_e32 v232, v232, v248
	v_add_f32_e32 v233, v233, v249
	v_add_f32_e32 v234, v234, v250
	v_add_f32_e32 v235, v235, v251
	v_add_f32_e32 v236, v236, v252
	v_add_f32_e32 v237, v237, v253
	v_add_f32_e32 v238, v238, v210
	v_add_f32_e32 v239, v239, v211
	v_add_f32_e32 v240, v240, v212
	v_add_f32_e32 v241, v241, v213
	v_add_f32_e32 v242, v242, v144
	v_add_f32_e32 v243, v243, v255
	v_cndmask_b32_e64 v244, v182, v228, s[46:47]
	v_cndmask_b32_e64 v245, v182, v229, s[48:49]
	v_cndmask_b32_e64 v246, v182, v230, s[50:51]
	v_cndmask_b32_e64 v247, v182, v231, s[52:53]
	v_cndmask_b32_e64 v248, v182, v232, s[54:55]
	v_cndmask_b32_e64 v249, v182, v233, s[56:57]
	v_cndmask_b32_e64 v250, v182, v234, s[58:59]
	v_cndmask_b32_e64 v251, v182, v235, s[60:61]
	v_cndmask_b32_e64 v252, v182, v236, s[62:63]
	v_cndmask_b32_e64 v253, v182, v237, s[64:65]
	v_cndmask_b32_e64 v210, v182, v238, s[66:67]
	v_cndmask_b32_e64 v211, v182, v239, s[68:69]
	v_cndmask_b32_e64 v212, v182, v240, s[96:97]
	v_cndmask_b32_e64 v213, v182, v241, s[98:99]
	v_cndmask_b32_e64 v144, v182, v242, s[100:101]
	v_cndmask_b32_e64 v255, v182, v243, s[22:23]
	v_max3_f32 v244, v244, v245, v246
	v_max3_f32 v247, v247, v248, v249
	v_max3_f32 v250, v250, v251, v252
	v_max3_f32 v253, v253, v210, v211
	v_max3_f32 v212, v212, v213, v144
	v_max3_f32 v244, v244, v247, v250
	v_max3_f32 v253, v253, v212, v255
	v_max_f32_e32 v244, v244, v253
	v_mov_b32_e32 v127, v244
	s_nop 1
	v_permlane16_swap_b32_e32 v244, v127
	v_max_f32_e32 v244, v244, v127
	v_mov_b32_e32 v127, v244
	s_nop 1
	v_permlane32_swap_b32_e32 v244, v127
	v_max3_f32 v214, v103, v244, v127
	v_sub_f32_e32 v150, v103, v214
	v_sub_f32_e32 v228, v228, v214
	v_sub_f32_e32 v229, v229, v214
	v_sub_f32_e32 v230, v230, v214
	v_sub_f32_e32 v231, v231, v214
	v_sub_f32_e32 v232, v232, v214
	v_sub_f32_e32 v233, v233, v214
	v_sub_f32_e32 v234, v234, v214
	v_sub_f32_e32 v235, v235, v214
	v_sub_f32_e32 v236, v236, v214
	v_sub_f32_e32 v237, v237, v214
	v_sub_f32_e32 v238, v238, v214
	v_sub_f32_e32 v239, v239, v214
	v_sub_f32_e32 v240, v240, v214
	v_sub_f32_e32 v241, v241, v214
	v_sub_f32_e32 v242, v242, v214
	v_sub_f32_e32 v243, v243, v214
	v_mul_f32_e32 v150, 0x3fb8aa3b, v150
	v_mul_f32_e32 v228, 0x3fb8aa3b, v228
	v_mul_f32_e32 v229, 0x3fb8aa3b, v229
	v_mul_f32_e32 v230, 0x3fb8aa3b, v230
	v_mul_f32_e32 v231, 0x3fb8aa3b, v231
	v_mul_f32_e32 v232, 0x3fb8aa3b, v232
	v_mul_f32_e32 v233, 0x3fb8aa3b, v233
	v_mul_f32_e32 v234, 0x3fb8aa3b, v234
	v_mul_f32_e32 v235, 0x3fb8aa3b, v235
	v_mul_f32_e32 v236, 0x3fb8aa3b, v236
	v_mul_f32_e32 v237, 0x3fb8aa3b, v237
	v_mul_f32_e32 v238, 0x3fb8aa3b, v238
	v_mul_f32_e32 v239, 0x3fb8aa3b, v239
	v_mul_f32_e32 v240, 0x3fb8aa3b, v240
	v_mul_f32_e32 v241, 0x3fb8aa3b, v241
	v_mul_f32_e32 v242, 0x3fb8aa3b, v242
	v_mul_f32_e32 v243, 0x3fb8aa3b, v243
	v_exp_f32_e32 v150, v150
	v_exp_f32_e32 v228, v228
	v_exp_f32_e32 v229, v229
	v_exp_f32_e32 v230, v230
	v_exp_f32_e32 v231, v231
	v_exp_f32_e32 v232, v232
	v_exp_f32_e32 v233, v233
	v_exp_f32_e32 v234, v234
	v_exp_f32_e32 v235, v235
	v_exp_f32_e32 v236, v236
	v_exp_f32_e32 v237, v237
	v_exp_f32_e32 v238, v238
	v_exp_f32_e32 v239, v239
	v_exp_f32_e32 v240, v240
	v_exp_f32_e32 v241, v241
	v_exp_f32_e32 v242, v242
	v_exp_f32_e32 v243, v243
	v_mov_b32_e32 v103, v214
	v_cndmask_b32_e64 v228, 0, v228, s[46:47]
	v_cndmask_b32_e64 v229, 0, v229, s[48:49]
	v_cndmask_b32_e64 v230, 0, v230, s[50:51]
	v_cndmask_b32_e64 v231, 0, v231, s[52:53]
	v_cndmask_b32_e64 v232, 0, v232, s[54:55]
	v_cndmask_b32_e64 v233, 0, v233, s[56:57]
	v_cndmask_b32_e64 v234, 0, v234, s[58:59]
	v_cndmask_b32_e64 v235, 0, v235, s[60:61]
	v_cndmask_b32_e64 v236, 0, v236, s[62:63]
	v_cndmask_b32_e64 v237, 0, v237, s[64:65]
	v_cndmask_b32_e64 v238, 0, v238, s[66:67]
	v_cndmask_b32_e64 v239, 0, v239, s[68:69]
	v_cndmask_b32_e64 v240, 0, v240, s[96:97]
	v_cndmask_b32_e64 v241, 0, v241, s[98:99]
	v_cndmask_b32_e64 v242, 0, v242, s[100:101]
	v_cndmask_b32_e64 v243, 0, v243, s[22:23]
	v_pk_mul_f32 v[38:39], v[38:39], v[150:151] op_sel_hi:[1,0]
	v_pk_mul_f32 v[36:37], v[36:37], v[150:151] op_sel_hi:[1,0]
	v_pk_mul_f32 v[34:35], v[34:35], v[150:151] op_sel_hi:[1,0]
	v_pk_mul_f32 v[32:33], v[32:33], v[150:151] op_sel_hi:[1,0]
	v_pk_mul_f32 v[30:31], v[30:31], v[150:151] op_sel_hi:[1,0]
	v_pk_mul_f32 v[28:29], v[28:29], v[150:151] op_sel_hi:[1,0]
	v_pk_mul_f32 v[26:27], v[26:27], v[150:151] op_sel_hi:[1,0]
	v_pk_mul_f32 v[24:25], v[24:25], v[150:151] op_sel_hi:[1,0]
	v_add_f32_e32 v127, v229, v228
	v_add_f32_e32 v127, v230, v127
	v_add_f32_e32 v127, v231, v127
	v_add_f32_e32 v127, v232, v127
	v_add_f32_e32 v127, v233, v127
	v_add_f32_e32 v127, v234, v127
	v_add_f32_e32 v127, v235, v127
	v_add_f32_e32 v127, v236, v127
	v_add_f32_e32 v127, v237, v127
	v_add_f32_e32 v127, v238, v127
	v_add_f32_e32 v127, v239, v127
	v_add_f32_e32 v127, v240, v127
	v_add_f32_e32 v127, v241, v127
	v_add_f32_e32 v127, v242, v127
	v_add_f32_e32 v127, v243, v127
	v_fmac_f32_e32 v127, v126, v150
	v_cvt_pk_bf16_f32 v244, v228, v229
	v_cvt_pk_bf16_f32 v245, v230, v231
	v_cvt_pk_bf16_f32 v246, v232, v233
	v_cvt_pk_bf16_f32 v247, v234, v235
	v_cvt_pk_bf16_f32 v248, v236, v237
	v_cvt_pk_bf16_f32 v249, v238, v239
	v_cvt_pk_bf16_f32 v250, v240, v241
	v_cvt_pk_bf16_f32 v251, v242, v243
	v_mov_b32_e32 v126, v127
	s_cmp_lt_i32 s0, s21
	s_cbranch_scc0 .Lwin_last
	s_waitcnt vmcnt(8)
	v_mfma_f32_16x16x32_bf16 v[36:39], v[72:75], v[244:247], v[36:39]
	v_mfma_f32_16x16x32_bf16 v[32:35], v[80:83], v[244:247], v[32:35]
	v_mfma_f32_16x16x32_bf16 v[28:31], v[108:111], v[244:247], v[28:31]
	v_mfma_f32_16x16x32_bf16 v[24:27], v[116:119], v[244:247], v[24:27]
	v_mfma_f32_16x16x32_bf16 v[36:39], v[76:79], v[248:251], v[36:39]
	v_mfma_f32_16x16x32_bf16 v[32:35], v[104:107], v[248:251], v[32:35]
	v_mfma_f32_16x16x32_bf16 v[28:31], v[112:115], v[248:251], v[28:31]
	v_mfma_f32_16x16x32_bf16 v[24:27], v[120:123], v[248:251], v[24:27]
	global_load_dwordx4 v[72:75], v[124:125], off offset:-4096
	global_load_dwordx4 v[76:79], v[124:125], off offset:-3072
	global_load_dwordx4 v[80:83], v[124:125], off offset:-2048
	global_load_dwordx4 v[104:107], v[124:125], off offset:-1024
	global_load_dwordx4 v[108:111], v[124:125], off offset:0
	global_load_dwordx4 v[112:115], v[124:125], off offset:1024
	global_load_dwordx4 v[116:119], v[124:125], off offset:2048
	global_load_dwordx4 v[120:123], v[124:125], off offset:3072
	s_branch .Lwin_loop
; __device__ __forceinline__ void nsa_wave(CArgs* Ap, int l, int b, int g, int tq0, const LAS float* lut, LAS float* imp, int lane) {
;     ...
;             pv_acc(Od, vf, pB);
;         }
;         float lt = st.l; lt += __shfl_xor(lt, 16); lt += __shfl_xor(lt, 32);
.Lwin_last:
	s_waitcnt vmcnt(0)
	s_nop 0
	v_mfma_f32_16x16x32_bf16 v[36:39], v[72:75], v[244:247], v[36:39]
	v_mfma_f32_16x16x32_bf16 v[32:35], v[80:83], v[244:247], v[32:35]
	v_mfma_f32_16x16x32_bf16 v[28:31], v[108:111], v[244:247], v[28:31]
	v_mfma_f32_16x16x32_bf16 v[24:27], v[116:119], v[244:247], v[24:27]
	v_mfma_f32_16x16x32_bf16 v[36:39], v[76:79], v[248:251], v[36:39]
	v_mfma_f32_16x16x32_bf16 v[32:35], v[104:107], v[248:251], v[32:35]
	v_mfma_f32_16x16x32_bf16 v[28:31], v[112:115], v[248:251], v[28:31]
	v_mfma_f32_16x16x32_bf16 v[24:27], v[120:123], v[248:251], v[24:27]
	v_mov_b32_e32 v72, v126
	s_branch .LBB0_892

; __global__ void __launch_bounds__(512, 2) hymba_fwd(Args A_unused) {
	.amdhsa_kernel _Z9hymba_fwd4Args
		.amdhsa_group_segment_fixed_size 0
		.amdhsa_private_segment_fixed_size 0
		.amdhsa_kernarg_size 480
		.amdhsa_user_sgpr_count 2
		.amdhsa_user_sgpr_dispatch_ptr 0
		.amdhsa_user_sgpr_queue_ptr 0
		.amdhsa_user_sgpr_kernarg_segment_ptr 1
		.amdhsa_user_sgpr_dispatch_id 0
		.amdhsa_user_sgpr_kernarg_preload_length 0
		.amdhsa_user_sgpr_kernarg_preload_offset 0
		.amdhsa_user_sgpr_private_segment_size 0
		.amdhsa_uses_dynamic_stack 0
		.amdhsa_enable_private_segment 0
		.amdhsa_system_sgpr_workgroup_id_x 1
		.amdhsa_system_sgpr_workgroup_id_y 0
		.amdhsa_system_sgpr_workgroup_id_z 0
		.amdhsa_system_sgpr_workgroup_info 0
		.amdhsa_system_vgpr_workitem_id 2
		.amdhsa_next_free_vgpr 256
		.amdhsa_next_free_sgpr 102
		.amdhsa_accum_offset 256
		.amdhsa_reserve_vcc 1
		.amdhsa_float_round_mode_32 0
		.amdhsa_float_round_mode_16_64 0
		.amdhsa_float_denorm_mode_32 3
		.amdhsa_float_denorm_mode_16_64 3
		.amdhsa_dx10_clamp 1
		.amdhsa_ieee_mode 1
		.amdhsa_fp16_overflow 0
		.amdhsa_tg_split 0
		.amdhsa_exception_fp_ieee_invalid_op 0
		.amdhsa_exception_fp_denorm_src 0
		.amdhsa_exception_fp_ieee_div_zero 0
		.amdhsa_exception_fp_ieee_overflow 0
		.amdhsa_exception_fp_ieee_underflow 0
		.amdhsa_exception_fp_ieee_inexact 0
		.amdhsa_exception_int_div_zero 0
	.end_amdhsa_kernel

; __global__ void __launch_bounds__(512, 2) hymba_fwd(Args A_unused) {
amdhsa.kernels:
  - .agpr_count:     0
    .args:
      - .offset:         0
        .size:           224
        .value_kind:     by_value
      - .offset:         224
        .size:           4
        .value_kind:     hidden_block_count_x
      - .offset:         228
        .size:           4
        .value_kind:     hidden_block_count_y
      - .offset:         232
        .size:           4
        .value_kind:     hidden_block_count_z
      - .offset:         236
        .size:           2
        .value_kind:     hidden_group_size_x
      - .offset:         238
        .size:           2
        .value_kind:     hidden_group_size_y
      - .offset:         240
        .size:           2
        .value_kind:     hidden_group_size_z
      - .offset:         242
        .size:           2
        .value_kind:     hidden_remainder_x
      - .offset:         244
        .size:           2
        .value_kind:     hidden_remainder_y
      - .offset:         246
        .size:           2
        .value_kind:     hidden_remainder_z
      - .offset:         264
        .size:           8
        .value_kind:     hidden_global_offset_x
      - .offset:         272
        .size:           8
        .value_kind:     hidden_global_offset_y
      - .offset:         280
        .size:           8
        .value_kind:     hidden_global_offset_z
      - .offset:         288
        .size:           2
        .value_kind:     hidden_grid_dims
      - .offset:         312
        .size:           8
        .value_kind:     hidden_multigrid_sync_arg
      - .offset:         344
        .size:           4
        .value_kind:     hidden_dynamic_lds_size
    .group_segment_fixed_size: 0
    .kernarg_segment_align: 8
    .kernarg_segment_size: 480
    .language:       OpenCL C
    .language_version:
      - 2
      - 0
    .max_flat_workgroup_size: 512
    .name:           _Z9hymba_fwd4Args
    .private_segment_fixed_size: 0
    .sgpr_count:     108
    .sgpr_spill_count: 43
    .symbol:         _Z9hymba_fwd4Args.kd
    .uniform_work_group_size: 1
    .uses_dynamic_stack: false
    .vgpr_count:     256
    .vgpr_spill_count: 0
    .wavefront_size: 64
